# c4 plus nt hint on P3 x1 stores and P0 bf16 weight/x stores
# speedup vs baseline: 1.0008x; 1.0008x over previous
.LBB0_204:
	s_waitcnt vmcnt(0)
	v_pk_mul_f32 v[166:167], v[0:1], v[32:33] op_sel_hi:[0,1]
	ds_write2_b32 v174, v166, v167 offset1:1
	v_pk_mul_f32 v[166:167], v[0:1], v[34:35] op_sel_hi:[0,1]
	ds_write2_b32 v174, v166, v167 offset0:2 offset1:3
	v_pk_mul_f32 v[166:167], v[0:1], v[36:37] op_sel:[1,0]
	v_add_u32_e32 v168, 0x410, v174
	ds_write2_b32 v168, v166, v167 offset1:1
	v_pk_mul_f32 v[166:167], v[0:1], v[38:39] op_sel:[1,0]
	v_add_u32_e32 v168, 0x418, v174
	ds_write2_b32 v168, v166, v167 offset1:1
	v_pk_mul_f32 v[166:167], v[2:3], v[40:41] op_sel_hi:[0,1]
	v_add_u32_e32 v168, 0x820, v174
	ds_write2_b32 v168, v166, v167 offset1:1
	v_pk_mul_f32 v[166:167], v[2:3], v[42:43] op_sel_hi:[0,1]
	v_add_u32_e32 v168, 0x828, v174
	ds_write2_b32 v168, v166, v167 offset1:1
	v_mov_b32_e32 v166, v3
	v_pk_mul_f32 v[168:169], v[166:167], v[44:45] op_sel_hi:[0,1]
	v_add_u32_e32 v167, 0xc30, v174
	ds_write2_b32 v167, v168, v169 offset1:1
	v_pk_mul_f32 v[166:167], v[166:167], v[46:47] op_sel_hi:[0,1]
	v_add_u32_e32 v168, 0xc38, v174
	ds_write2_b32 v168, v166, v167 offset1:1
	v_pk_mul_f32 v[166:167], v[4:5], v[48:49] op_sel_hi:[0,1]
	v_add_u32_e32 v168, 0x1040, v174
	ds_write2_b32 v168, v166, v167 offset1:1
	v_pk_mul_f32 v[166:167], v[4:5], v[50:51] op_sel_hi:[0,1]
	v_add_u32_e32 v168, 0x1048, v174
	ds_write2_b32 v168, v166, v167 offset1:1
	v_mov_b32_e32 v166, v5
	v_pk_mul_f32 v[168:169], v[166:167], v[52:53] op_sel_hi:[0,1]
	v_add_u32_e32 v167, 0x1450, v174
	ds_write2_b32 v167, v168, v169 offset1:1
	v_pk_mul_f32 v[166:167], v[166:167], v[54:55] op_sel_hi:[0,1]
	v_add_u32_e32 v168, 0x1458, v174
	ds_write2_b32 v168, v166, v167 offset1:1
	v_pk_mul_f32 v[166:167], v[6:7], v[56:57] op_sel_hi:[0,1]
	v_add_u32_e32 v168, 0x1860, v174
	ds_write2_b32 v168, v166, v167 offset1:1
	v_pk_mul_f32 v[166:167], v[6:7], v[58:59] op_sel_hi:[0,1]
	v_add_u32_e32 v168, 0x1868, v174
	ds_write2_b32 v168, v166, v167 offset1:1
	v_mov_b32_e32 v166, v7
	v_pk_mul_f32 v[168:169], v[166:167], v[60:61] op_sel_hi:[0,1]
	v_add_u32_e32 v167, 0x1c70, v174
	ds_write2_b32 v167, v168, v169 offset1:1
	v_pk_mul_f32 v[166:167], v[166:167], v[62:63] op_sel_hi:[0,1]
	v_add_u32_e32 v168, 0x1c78, v174
	ds_write2_b32 v168, v166, v167 offset1:1
	v_pk_mul_f32 v[166:167], v[8:9], v[64:65] op_sel_hi:[0,1]
	v_add_u32_e32 v168, 0x2080, v174
	ds_write2_b32 v168, v166, v167 offset1:1
	v_pk_mul_f32 v[166:167], v[8:9], v[66:67] op_sel_hi:[0,1]
	v_add_u32_e32 v168, 0x2088, v174
	ds_write2_b32 v168, v166, v167 offset1:1
	v_mov_b32_e32 v166, v9
	v_pk_mul_f32 v[168:169], v[166:167], v[68:69] op_sel_hi:[0,1]
	v_add_u32_e32 v167, 0x2490, v174
	ds_write2_b32 v167, v168, v169 offset1:1
	v_pk_mul_f32 v[166:167], v[166:167], v[70:71] op_sel_hi:[0,1]
	v_add_u32_e32 v168, 0x2498, v174
	ds_write2_b32 v168, v166, v167 offset1:1
	v_pk_mul_f32 v[166:167], v[10:11], v[72:73] op_sel_hi:[0,1]
	v_add_u32_e32 v168, 0x28a0, v174
	ds_write2_b32 v168, v166, v167 offset1:1
	v_pk_mul_f32 v[166:167], v[10:11], v[74:75] op_sel_hi:[0,1]
	v_add_u32_e32 v168, 0x28a8, v174
	ds_write2_b32 v168, v166, v167 offset1:1
	v_mov_b32_e32 v166, v11
	v_pk_mul_f32 v[168:169], v[166:167], v[76:77] op_sel_hi:[0,1]
	v_add_u32_e32 v167, 0x2cb0, v174
	ds_write2_b32 v167, v168, v169 offset1:1
	v_pk_mul_f32 v[166:167], v[166:167], v[78:79] op_sel_hi:[0,1]
	v_add_u32_e32 v168, 0x2cb8, v174
	ds_write2_b32 v168, v166, v167 offset1:1
	v_pk_mul_f32 v[166:167], v[12:13], v[80:81] op_sel_hi:[0,1]
	v_add_u32_e32 v168, 0x30c0, v174
	ds_write2_b32 v168, v166, v167 offset1:1
	v_pk_mul_f32 v[166:167], v[12:13], v[82:83] op_sel_hi:[0,1]
	v_add_u32_e32 v168, 0x30c8, v174
	ds_write2_b32 v168, v166, v167 offset1:1
	v_mov_b32_e32 v166, v13
	v_pk_mul_f32 v[168:169], v[166:167], v[84:85] op_sel_hi:[0,1]
	v_add_u32_e32 v167, 0x34d0, v174
	ds_write2_b32 v167, v168, v169 offset1:1
	v_pk_mul_f32 v[166:167], v[166:167], v[86:87] op_sel_hi:[0,1]
	v_add_u32_e32 v168, 0x34d8, v174
	ds_write2_b32 v168, v166, v167 offset1:1
	v_pk_mul_f32 v[166:167], v[14:15], v[88:89] op_sel_hi:[0,1]
	v_add_u32_e32 v168, 0x38e0, v174
	ds_write2_b32 v168, v166, v167 offset1:1
	v_pk_mul_f32 v[166:167], v[14:15], v[90:91] op_sel_hi:[0,1]
	v_add_u32_e32 v168, 0x38e8, v174
	ds_write2_b32 v168, v166, v167 offset1:1
	v_mov_b32_e32 v166, v15
	v_pk_mul_f32 v[168:169], v[166:167], v[92:93] op_sel_hi:[0,1]
	v_add_u32_e32 v167, 0x3cf0, v174
	ds_write2_b32 v167, v168, v169 offset1:1
	v_pk_mul_f32 v[166:167], v[166:167], v[94:95] op_sel_hi:[0,1]
	v_add_u32_e32 v168, 0x3cf8, v174
	ds_write2_b32 v168, v166, v167 offset1:1
	s_waitcnt lgkmcnt(0)
	v_add_u32_e32 v168, s24, v172
	v_cmp_gt_i32_e32 vcc, s20, v168
	v_add_u32_e32 v176, 0x400, v173
	v_lshlrev_b32_e32 v166, 1, v164
	s_and_saveexec_b64 s[2:3], vcc
	s_cbranch_execz .LBB0_206
	ds_read2_b32 v[170:171], v176 offset0:134 offset1:199
	ds_read2_b32 v[180:181], v176 offset0:4 offset1:69
	ds_read2_b32 v[178:179], v173 offset0:130 offset1:195
	ds_read2_b32 v[182:183], v173 offset1:65
	v_ashrrev_i32_e32 v169, 31, v168
	v_lshlrev_b64 v[184:185], 12, v[168:169]
	v_lshl_add_u64 v[184:185], s[28:29], 0, v[184:185]
	s_ashr_i32 s23, s22, 31
	v_lshl_add_u64 v[184:185], s[22:23], 1, v[184:185]
	v_mov_b32_e32 v167, v163
	v_lshl_add_u64 v[184:185], v[184:185], 0, v[166:167]
	s_waitcnt lgkmcnt(1)
	v_and_b32_sdwa v167, v179, v175 dst_sel:DWORD dst_unused:UNUSED_PAD src0_sel:WORD_1 src1_sel:DWORD
	s_waitcnt lgkmcnt(0)
	v_and_b32_sdwa v169, v183, v175 dst_sel:DWORD dst_unused:UNUSED_PAD src0_sel:WORD_1 src1_sel:DWORD
	v_add3_u32 v167, v179, v167, s21
	v_add3_u32 v169, v183, v169, s21
	v_and_b32_sdwa v177, v178, v175 dst_sel:DWORD dst_unused:UNUSED_PAD src0_sel:WORD_1 src1_sel:DWORD
	v_and_b32_sdwa v179, v182, v175 dst_sel:DWORD dst_unused:UNUSED_PAD src0_sel:WORD_1 src1_sel:DWORD
	v_and_b32_e32 v167, 0xffff0000, v167
	v_and_b32_e32 v169, 0xffff0000, v169
	v_add3_u32 v182, v182, v179, s21
	v_add3_u32 v177, v178, v177, s21
	v_or_b32_sdwa v179, v177, v167 dst_sel:DWORD dst_unused:UNUSED_PAD src0_sel:WORD_1 src1_sel:DWORD
	v_or_b32_sdwa v178, v182, v169 dst_sel:DWORD dst_unused:UNUSED_PAD src0_sel:WORD_1 src1_sel:DWORD
	v_and_b32_sdwa v167, v171, v175 dst_sel:DWORD dst_unused:UNUSED_PAD src0_sel:WORD_1 src1_sel:DWORD
	v_and_b32_sdwa v169, v181, v175 dst_sel:DWORD dst_unused:UNUSED_PAD src0_sel:WORD_1 src1_sel:DWORD
	v_add3_u32 v167, v171, v167, s21
	v_add3_u32 v169, v181, v169, s21
	v_and_b32_sdwa v171, v170, v175 dst_sel:DWORD dst_unused:UNUSED_PAD src0_sel:WORD_1 src1_sel:DWORD
	v_and_b32_sdwa v177, v180, v175 dst_sel:DWORD dst_unused:UNUSED_PAD src0_sel:WORD_1 src1_sel:DWORD
	v_and_b32_e32 v167, 0xffff0000, v167
	v_and_b32_e32 v169, 0xffff0000, v169
	v_add3_u32 v177, v180, v177, s21
	v_add3_u32 v170, v170, v171, s21
	v_or_b32_sdwa v181, v170, v167 dst_sel:DWORD dst_unused:UNUSED_PAD src0_sel:WORD_1 src1_sel:DWORD
	v_or_b32_sdwa v180, v177, v169 dst_sel:DWORD dst_unused:UNUSED_PAD src0_sel:WORD_1 src1_sel:DWORD
	global_store_dwordx4 v[184:185], v[178:181], off nt
.LBB0_206:
	s_or_b64 exec, exec, s[2:3]
	v_add_u32_e32 v170, 8, v168
	v_cmp_gt_i32_e32 vcc, s20, v170
	s_and_saveexec_b64 s[2:3], vcc
	s_cbranch_execz .LBB0_208
	ds_read2_b32 v[180:181], v176 offset0:142 offset1:207
	ds_read2_b32 v[182:183], v176 offset0:12 offset1:77
	ds_read2_b32 v[178:179], v173 offset0:138 offset1:203
	ds_read2_b32 v[184:185], v173 offset0:8 offset1:73
	v_ashrrev_i32_e32 v171, 31, v170
	v_lshlrev_b64 v[170:171], 12, v[170:171]
	v_lshl_add_u64 v[170:171], s[28:29], 0, v[170:171]
	s_ashr_i32 s23, s22, 31
	v_lshl_add_u64 v[170:171], s[22:23], 1, v[170:171]
	v_mov_b32_e32 v167, v163
	v_lshl_add_u64 v[170:171], v[170:171], 0, v[166:167]
	s_waitcnt lgkmcnt(1)
	v_and_b32_sdwa v167, v179, v175 dst_sel:DWORD dst_unused:UNUSED_PAD src0_sel:WORD_1 src1_sel:DWORD
	s_waitcnt lgkmcnt(0)
	v_and_b32_sdwa v169, v185, v175 dst_sel:DWORD dst_unused:UNUSED_PAD src0_sel:WORD_1 src1_sel:DWORD
	v_add3_u32 v167, v179, v167, s21
	v_add3_u32 v169, v185, v169, s21
	v_and_b32_sdwa v177, v178, v175 dst_sel:DWORD dst_unused:UNUSED_PAD src0_sel:WORD_1 src1_sel:DWORD
	v_and_b32_sdwa v179, v184, v175 dst_sel:DWORD dst_unused:UNUSED_PAD src0_sel:WORD_1 src1_sel:DWORD
	v_and_b32_e32 v167, 0xffff0000, v167
	v_and_b32_e32 v169, 0xffff0000, v169
	v_add3_u32 v184, v184, v179, s21
	v_add3_u32 v177, v178, v177, s21
	v_or_b32_sdwa v179, v177, v167 dst_sel:DWORD dst_unused:UNUSED_PAD src0_sel:WORD_1 src1_sel:DWORD
	v_or_b32_sdwa v178, v184, v169 dst_sel:DWORD dst_unused:UNUSED_PAD src0_sel:WORD_1 src1_sel:DWORD
	v_and_b32_sdwa v167, v181, v175 dst_sel:DWORD dst_unused:UNUSED_PAD src0_sel:WORD_1 src1_sel:DWORD
	v_and_b32_sdwa v169, v183, v175 dst_sel:DWORD dst_unused:UNUSED_PAD src0_sel:WORD_1 src1_sel:DWORD
	v_add3_u32 v167, v181, v167, s21
	v_add3_u32 v169, v183, v169, s21
	v_and_b32_sdwa v177, v180, v175 dst_sel:DWORD dst_unused:UNUSED_PAD src0_sel:WORD_1 src1_sel:DWORD
	v_and_b32_sdwa v181, v182, v175 dst_sel:DWORD dst_unused:UNUSED_PAD src0_sel:WORD_1 src1_sel:DWORD
	v_and_b32_e32 v167, 0xffff0000, v167
	v_and_b32_e32 v169, 0xffff0000, v169
	v_add3_u32 v182, v182, v181, s21
	v_add3_u32 v177, v180, v177, s21
	v_or_b32_sdwa v181, v177, v167 dst_sel:DWORD dst_unused:UNUSED_PAD src0_sel:WORD_1 src1_sel:DWORD
	v_or_b32_sdwa v180, v182, v169 dst_sel:DWORD dst_unused:UNUSED_PAD src0_sel:WORD_1 src1_sel:DWORD
	global_store_dwordx4 v[170:171], v[178:181], off nt
.LBB0_208:
	s_or_b64 exec, exec, s[2:3]
	v_add_u32_e32 v170, 16, v168
	v_cmp_gt_i32_e32 vcc, s20, v170
	s_and_saveexec_b64 s[2:3], vcc
	s_cbranch_execz .LBB0_210
	ds_read2_b32 v[180:181], v176 offset0:150 offset1:215
	ds_read2_b32 v[182:183], v176 offset0:20 offset1:85
	ds_read2_b32 v[178:179], v173 offset0:146 offset1:211
	ds_read2_b32 v[184:185], v173 offset0:16 offset1:81
	v_ashrrev_i32_e32 v171, 31, v170
	v_lshlrev_b64 v[170:171], 12, v[170:171]
	v_lshl_add_u64 v[170:171], s[28:29], 0, v[170:171]
	s_ashr_i32 s23, s22, 31
	v_lshl_add_u64 v[170:171], s[22:23], 1, v[170:171]
	v_mov_b32_e32 v167, v163
	v_lshl_add_u64 v[170:171], v[170:171], 0, v[166:167]
	s_waitcnt lgkmcnt(1)
	v_and_b32_sdwa v167, v179, v175 dst_sel:DWORD dst_unused:UNUSED_PAD src0_sel:WORD_1 src1_sel:DWORD
	s_waitcnt lgkmcnt(0)
	v_and_b32_sdwa v169, v185, v175 dst_sel:DWORD dst_unused:UNUSED_PAD src0_sel:WORD_1 src1_sel:DWORD
	v_add3_u32 v167, v179, v167, s21
	v_add3_u32 v169, v185, v169, s21
	v_and_b32_sdwa v177, v178, v175 dst_sel:DWORD dst_unused:UNUSED_PAD src0_sel:WORD_1 src1_sel:DWORD
	v_and_b32_sdwa v179, v184, v175 dst_sel:DWORD dst_unused:UNUSED_PAD src0_sel:WORD_1 src1_sel:DWORD
	v_and_b32_e32 v167, 0xffff0000, v167
	v_and_b32_e32 v169, 0xffff0000, v169
	v_add3_u32 v184, v184, v179, s21
	v_add3_u32 v177, v178, v177, s21
	v_or_b32_sdwa v179, v177, v167 dst_sel:DWORD dst_unused:UNUSED_PAD src0_sel:WORD_1 src1_sel:DWORD
	v_or_b32_sdwa v178, v184, v169 dst_sel:DWORD dst_unused:UNUSED_PAD src0_sel:WORD_1 src1_sel:DWORD
	v_and_b32_sdwa v167, v181, v175 dst_sel:DWORD dst_unused:UNUSED_PAD src0_sel:WORD_1 src1_sel:DWORD
	v_and_b32_sdwa v169, v183, v175 dst_sel:DWORD dst_unused:UNUSED_PAD src0_sel:WORD_1 src1_sel:DWORD
	v_add3_u32 v167, v181, v167, s21
	v_add3_u32 v169, v183, v169, s21
	v_and_b32_sdwa v177, v180, v175 dst_sel:DWORD dst_unused:UNUSED_PAD src0_sel:WORD_1 src1_sel:DWORD
	v_and_b32_sdwa v181, v182, v175 dst_sel:DWORD dst_unused:UNUSED_PAD src0_sel:WORD_1 src1_sel:DWORD
	v_and_b32_e32 v167, 0xffff0000, v167
	v_and_b32_e32 v169, 0xffff0000, v169
	v_add3_u32 v182, v182, v181, s21
	v_add3_u32 v177, v180, v177, s21
	v_or_b32_sdwa v181, v177, v167 dst_sel:DWORD dst_unused:UNUSED_PAD src0_sel:WORD_1 src1_sel:DWORD
	v_or_b32_sdwa v180, v182, v169 dst_sel:DWORD dst_unused:UNUSED_PAD src0_sel:WORD_1 src1_sel:DWORD
	global_store_dwordx4 v[170:171], v[178:181], off nt
.LBB0_210:
	s_or_b64 exec, exec, s[2:3]
	v_add_u32_e32 v170, 24, v168
	v_cmp_gt_i32_e32 vcc, s20, v170
	s_and_saveexec_b64 s[2:3], vcc
	s_cbranch_execz .LBB0_212
	ds_read2_b32 v[180:181], v176 offset0:158 offset1:223
	ds_read2_b32 v[182:183], v176 offset0:28 offset1:93
	ds_read2_b32 v[178:179], v173 offset0:154 offset1:219
	ds_read2_b32 v[184:185], v173 offset0:24 offset1:89
	v_ashrrev_i32_e32 v171, 31, v170
	v_lshlrev_b64 v[170:171], 12, v[170:171]
	v_lshl_add_u64 v[170:171], s[28:29], 0, v[170:171]
	s_ashr_i32 s23, s22, 31
	v_lshl_add_u64 v[170:171], s[22:23], 1, v[170:171]
	v_mov_b32_e32 v167, v163
	v_lshl_add_u64 v[170:171], v[170:171], 0, v[166:167]
	s_waitcnt lgkmcnt(1)
	v_and_b32_sdwa v167, v179, v175 dst_sel:DWORD dst_unused:UNUSED_PAD src0_sel:WORD_1 src1_sel:DWORD
	s_waitcnt lgkmcnt(0)
	v_and_b32_sdwa v169, v185, v175 dst_sel:DWORD dst_unused:UNUSED_PAD src0_sel:WORD_1 src1_sel:DWORD
	v_add3_u32 v167, v179, v167, s21
	v_add3_u32 v169, v185, v169, s21
	v_and_b32_sdwa v177, v178, v175 dst_sel:DWORD dst_unused:UNUSED_PAD src0_sel:WORD_1 src1_sel:DWORD
	v_and_b32_sdwa v179, v184, v175 dst_sel:DWORD dst_unused:UNUSED_PAD src0_sel:WORD_1 src1_sel:DWORD
	v_and_b32_e32 v167, 0xffff0000, v167
	v_and_b32_e32 v169, 0xffff0000, v169
	v_add3_u32 v184, v184, v179, s21
	v_add3_u32 v177, v178, v177, s21
	v_or_b32_sdwa v179, v177, v167 dst_sel:DWORD dst_unused:UNUSED_PAD src0_sel:WORD_1 src1_sel:DWORD
	v_or_b32_sdwa v178, v184, v169 dst_sel:DWORD dst_unused:UNUSED_PAD src0_sel:WORD_1 src1_sel:DWORD
	v_and_b32_sdwa v167, v181, v175 dst_sel:DWORD dst_unused:UNUSED_PAD src0_sel:WORD_1 src1_sel:DWORD
	v_and_b32_sdwa v169, v183, v175 dst_sel:DWORD dst_unused:UNUSED_PAD src0_sel:WORD_1 src1_sel:DWORD
	v_add3_u32 v167, v181, v167, s21
	v_add3_u32 v169, v183, v169, s21
	v_and_b32_sdwa v177, v180, v175 dst_sel:DWORD dst_unused:UNUSED_PAD src0_sel:WORD_1 src1_sel:DWORD
	v_and_b32_sdwa v181, v182, v175 dst_sel:DWORD dst_unused:UNUSED_PAD src0_sel:WORD_1 src1_sel:DWORD
	v_and_b32_e32 v167, 0xffff0000, v167
	v_and_b32_e32 v169, 0xffff0000, v169
	v_add3_u32 v182, v182, v181, s21
	v_add3_u32 v177, v180, v177, s21
	v_or_b32_sdwa v181, v177, v167 dst_sel:DWORD dst_unused:UNUSED_PAD src0_sel:WORD_1 src1_sel:DWORD
	v_or_b32_sdwa v180, v182, v169 dst_sel:DWORD dst_unused:UNUSED_PAD src0_sel:WORD_1 src1_sel:DWORD
	global_store_dwordx4 v[170:171], v[178:181], off nt
.LBB0_212:
	s_or_b64 exec, exec, s[2:3]
	v_add_u32_e32 v170, 32, v168
	v_cmp_gt_i32_e32 vcc, s20, v170
	s_and_saveexec_b64 s[2:3], vcc
	s_cbranch_execz .LBB0_214
	ds_read2_b32 v[180:181], v176 offset0:166 offset1:231
	ds_read2_b32 v[182:183], v176 offset0:36 offset1:101
	ds_read2_b32 v[178:179], v173 offset0:162 offset1:227
	ds_read2_b32 v[184:185], v173 offset0:32 offset1:97
	v_ashrrev_i32_e32 v171, 31, v170
	v_lshlrev_b64 v[170:171], 12, v[170:171]
	v_lshl_add_u64 v[170:171], s[28:29], 0, v[170:171]
	s_ashr_i32 s23, s22, 31
	v_lshl_add_u64 v[170:171], s[22:23], 1, v[170:171]
	v_mov_b32_e32 v167, v163
	v_lshl_add_u64 v[170:171], v[170:171], 0, v[166:167]
	s_waitcnt lgkmcnt(1)
	v_and_b32_sdwa v167, v179, v175 dst_sel:DWORD dst_unused:UNUSED_PAD src0_sel:WORD_1 src1_sel:DWORD
	s_waitcnt lgkmcnt(0)
	v_and_b32_sdwa v169, v185, v175 dst_sel:DWORD dst_unused:UNUSED_PAD src0_sel:WORD_1 src1_sel:DWORD
	v_add3_u32 v167, v179, v167, s21
	v_add3_u32 v169, v185, v169, s21
	v_and_b32_sdwa v177, v178, v175 dst_sel:DWORD dst_unused:UNUSED_PAD src0_sel:WORD_1 src1_sel:DWORD
	v_and_b32_sdwa v179, v184, v175 dst_sel:DWORD dst_unused:UNUSED_PAD src0_sel:WORD_1 src1_sel:DWORD
	v_and_b32_e32 v167, 0xffff0000, v167
	v_and_b32_e32 v169, 0xffff0000, v169
	v_add3_u32 v184, v184, v179, s21
	v_add3_u32 v177, v178, v177, s21
	v_or_b32_sdwa v179, v177, v167 dst_sel:DWORD dst_unused:UNUSED_PAD src0_sel:WORD_1 src1_sel:DWORD
	v_or_b32_sdwa v178, v184, v169 dst_sel:DWORD dst_unused:UNUSED_PAD src0_sel:WORD_1 src1_sel:DWORD
	v_and_b32_sdwa v167, v181, v175 dst_sel:DWORD dst_unused:UNUSED_PAD src0_sel:WORD_1 src1_sel:DWORD
	v_and_b32_sdwa v169, v183, v175 dst_sel:DWORD dst_unused:UNUSED_PAD src0_sel:WORD_1 src1_sel:DWORD
	v_add3_u32 v167, v181, v167, s21
	v_add3_u32 v169, v183, v169, s21
	v_and_b32_sdwa v177, v180, v175 dst_sel:DWORD dst_unused:UNUSED_PAD src0_sel:WORD_1 src1_sel:DWORD
	v_and_b32_sdwa v181, v182, v175 dst_sel:DWORD dst_unused:UNUSED_PAD src0_sel:WORD_1 src1_sel:DWORD
	v_and_b32_e32 v167, 0xffff0000, v167
	v_and_b32_e32 v169, 0xffff0000, v169
	v_add3_u32 v182, v182, v181, s21
	v_add3_u32 v177, v180, v177, s21
	v_or_b32_sdwa v181, v177, v167 dst_sel:DWORD dst_unused:UNUSED_PAD src0_sel:WORD_1 src1_sel:DWORD
	v_or_b32_sdwa v180, v182, v169 dst_sel:DWORD dst_unused:UNUSED_PAD src0_sel:WORD_1 src1_sel:DWORD
	global_store_dwordx4 v[170:171], v[178:181], off nt
.LBB0_214:
	s_or_b64 exec, exec, s[2:3]
	v_add_u32_e32 v170, 40, v168
	v_cmp_gt_i32_e32 vcc, s20, v170
	s_and_saveexec_b64 s[2:3], vcc
	s_cbranch_execz .LBB0_216
	ds_read2_b32 v[180:181], v176 offset0:174 offset1:239
	ds_read2_b32 v[182:183], v176 offset0:44 offset1:109
	ds_read2_b32 v[178:179], v173 offset0:170 offset1:235
	ds_read2_b32 v[184:185], v173 offset0:40 offset1:105
	v_ashrrev_i32_e32 v171, 31, v170
	v_lshlrev_b64 v[170:171], 12, v[170:171]
	v_lshl_add_u64 v[170:171], s[28:29], 0, v[170:171]
	s_ashr_i32 s23, s22, 31
	v_lshl_add_u64 v[170:171], s[22:23], 1, v[170:171]
	v_mov_b32_e32 v167, v163
	v_lshl_add_u64 v[170:171], v[170:171], 0, v[166:167]
	s_waitcnt lgkmcnt(1)
	v_and_b32_sdwa v167, v179, v175 dst_sel:DWORD dst_unused:UNUSED_PAD src0_sel:WORD_1 src1_sel:DWORD
	s_waitcnt lgkmcnt(0)
	v_and_b32_sdwa v169, v185, v175 dst_sel:DWORD dst_unused:UNUSED_PAD src0_sel:WORD_1 src1_sel:DWORD
	v_add3_u32 v167, v179, v167, s21
	v_add3_u32 v169, v185, v169, s21
	v_and_b32_sdwa v177, v178, v175 dst_sel:DWORD dst_unused:UNUSED_PAD src0_sel:WORD_1 src1_sel:DWORD
	v_and_b32_sdwa v179, v184, v175 dst_sel:DWORD dst_unused:UNUSED_PAD src0_sel:WORD_1 src1_sel:DWORD
	v_and_b32_e32 v167, 0xffff0000, v167
	v_and_b32_e32 v169, 0xffff0000, v169
	v_add3_u32 v184, v184, v179, s21
	v_add3_u32 v177, v178, v177, s21
	v_or_b32_sdwa v179, v177, v167 dst_sel:DWORD dst_unused:UNUSED_PAD src0_sel:WORD_1 src1_sel:DWORD
	v_or_b32_sdwa v178, v184, v169 dst_sel:DWORD dst_unused:UNUSED_PAD src0_sel:WORD_1 src1_sel:DWORD
	v_and_b32_sdwa v167, v181, v175 dst_sel:DWORD dst_unused:UNUSED_PAD src0_sel:WORD_1 src1_sel:DWORD
	v_and_b32_sdwa v169, v183, v175 dst_sel:DWORD dst_unused:UNUSED_PAD src0_sel:WORD_1 src1_sel:DWORD
	v_add3_u32 v167, v181, v167, s21
	v_add3_u32 v169, v183, v169, s21
	v_and_b32_sdwa v177, v180, v175 dst_sel:DWORD dst_unused:UNUSED_PAD src0_sel:WORD_1 src1_sel:DWORD
	v_and_b32_sdwa v181, v182, v175 dst_sel:DWORD dst_unused:UNUSED_PAD src0_sel:WORD_1 src1_sel:DWORD
	v_and_b32_e32 v167, 0xffff0000, v167
	v_and_b32_e32 v169, 0xffff0000, v169
	v_add3_u32 v182, v182, v181, s21
	v_add3_u32 v177, v180, v177, s21
	v_or_b32_sdwa v181, v177, v167 dst_sel:DWORD dst_unused:UNUSED_PAD src0_sel:WORD_1 src1_sel:DWORD
	v_or_b32_sdwa v180, v182, v169 dst_sel:DWORD dst_unused:UNUSED_PAD src0_sel:WORD_1 src1_sel:DWORD
	global_store_dwordx4 v[170:171], v[178:181], off nt
.LBB0_216:
	s_or_b64 exec, exec, s[2:3]
	v_add_u32_e32 v170, 48, v168
	v_cmp_gt_i32_e32 vcc, s20, v170
	s_and_saveexec_b64 s[2:3], vcc
	s_cbranch_execz .LBB0_218
	ds_read2_b32 v[180:181], v176 offset0:182 offset1:247
	ds_read2_b32 v[182:183], v176 offset0:52 offset1:117
	ds_read2_b32 v[178:179], v173 offset0:178 offset1:243
	ds_read2_b32 v[184:185], v173 offset0:48 offset1:113
	v_ashrrev_i32_e32 v171, 31, v170
	v_lshlrev_b64 v[170:171], 12, v[170:171]
	v_lshl_add_u64 v[170:171], s[28:29], 0, v[170:171]
	s_ashr_i32 s23, s22, 31
	v_lshl_add_u64 v[170:171], s[22:23], 1, v[170:171]
	v_mov_b32_e32 v167, v163
	v_lshl_add_u64 v[170:171], v[170:171], 0, v[166:167]
	s_waitcnt lgkmcnt(1)
	v_and_b32_sdwa v167, v179, v175 dst_sel:DWORD dst_unused:UNUSED_PAD src0_sel:WORD_1 src1_sel:DWORD
	s_waitcnt lgkmcnt(0)
	v_and_b32_sdwa v169, v185, v175 dst_sel:DWORD dst_unused:UNUSED_PAD src0_sel:WORD_1 src1_sel:DWORD
	v_add3_u32 v167, v179, v167, s21
	v_add3_u32 v169, v185, v169, s21
	v_and_b32_sdwa v177, v178, v175 dst_sel:DWORD dst_unused:UNUSED_PAD src0_sel:WORD_1 src1_sel:DWORD
	v_and_b32_sdwa v179, v184, v175 dst_sel:DWORD dst_unused:UNUSED_PAD src0_sel:WORD_1 src1_sel:DWORD
	v_and_b32_e32 v167, 0xffff0000, v167
	v_and_b32_e32 v169, 0xffff0000, v169
	v_add3_u32 v184, v184, v179, s21
	v_add3_u32 v177, v178, v177, s21
	v_or_b32_sdwa v179, v177, v167 dst_sel:DWORD dst_unused:UNUSED_PAD src0_sel:WORD_1 src1_sel:DWORD
	v_or_b32_sdwa v178, v184, v169 dst_sel:DWORD dst_unused:UNUSED_PAD src0_sel:WORD_1 src1_sel:DWORD
	v_and_b32_sdwa v167, v181, v175 dst_sel:DWORD dst_unused:UNUSED_PAD src0_sel:WORD_1 src1_sel:DWORD
	v_and_b32_sdwa v169, v183, v175 dst_sel:DWORD dst_unused:UNUSED_PAD src0_sel:WORD_1 src1_sel:DWORD
	v_add3_u32 v167, v181, v167, s21
	v_add3_u32 v169, v183, v169, s21
	v_and_b32_sdwa v177, v180, v175 dst_sel:DWORD dst_unused:UNUSED_PAD src0_sel:WORD_1 src1_sel:DWORD
	v_and_b32_sdwa v181, v182, v175 dst_sel:DWORD dst_unused:UNUSED_PAD src0_sel:WORD_1 src1_sel:DWORD
	v_and_b32_e32 v167, 0xffff0000, v167
	v_and_b32_e32 v169, 0xffff0000, v169
	v_add3_u32 v182, v182, v181, s21
	v_add3_u32 v177, v180, v177, s21
	v_or_b32_sdwa v181, v177, v167 dst_sel:DWORD dst_unused:UNUSED_PAD src0_sel:WORD_1 src1_sel:DWORD
	v_or_b32_sdwa v180, v182, v169 dst_sel:DWORD dst_unused:UNUSED_PAD src0_sel:WORD_1 src1_sel:DWORD
	global_store_dwordx4 v[170:171], v[178:181], off nt
.LBB0_218:
	s_or_b64 exec, exec, s[2:3]
	v_add_u32_e32 v168, 56, v168
	v_cmp_gt_i32_e32 vcc, s20, v168
	s_and_saveexec_b64 s[2:3], vcc
	s_cbranch_execz .LBB0_220
	ds_read2_b32 v[170:171], v176 offset0:190 offset1:255
	ds_read2_b32 v[176:177], v176 offset0:60 offset1:125
	ds_read2_b32 v[178:179], v173 offset0:186 offset1:251
	ds_read2_b32 v[180:181], v173 offset0:56 offset1:121
	v_ashrrev_i32_e32 v169, 31, v168
	v_lshlrev_b64 v[168:169], 12, v[168:169]
	v_lshl_add_u64 v[168:169], s[28:29], 0, v[168:169]
	s_ashr_i32 s23, s22, 31
	v_lshl_add_u64 v[168:169], s[22:23], 1, v[168:169]
	v_mov_b32_e32 v167, v163
	v_lshl_add_u64 v[182:183], v[168:169], 0, v[166:167]
	s_waitcnt lgkmcnt(0)
	v_and_b32_sdwa v167, v181, v175 dst_sel:DWORD dst_unused:UNUSED_PAD src0_sel:WORD_1 src1_sel:DWORD
	v_and_b32_sdwa v166, v179, v175 dst_sel:DWORD dst_unused:UNUSED_PAD src0_sel:WORD_1 src1_sel:DWORD
	v_add3_u32 v167, v181, v167, s21
	v_add3_u32 v166, v179, v166, s21
	v_and_b32_e32 v168, 0xffff0000, v167
	v_and_b32_sdwa v167, v178, v175 dst_sel:DWORD dst_unused:UNUSED_PAD src0_sel:WORD_1 src1_sel:DWORD
	v_and_b32_sdwa v169, v180, v175 dst_sel:DWORD dst_unused:UNUSED_PAD src0_sel:WORD_1 src1_sel:DWORD
	v_and_b32_e32 v166, 0xffff0000, v166
	v_add3_u32 v169, v180, v169, s21
	v_add3_u32 v167, v178, v167, s21
	v_or_b32_sdwa v167, v167, v166 dst_sel:DWORD dst_unused:UNUSED_PAD src0_sel:WORD_1 src1_sel:DWORD
	v_or_b32_sdwa v166, v169, v168 dst_sel:DWORD dst_unused:UNUSED_PAD src0_sel:WORD_1 src1_sel:DWORD
	v_and_b32_sdwa v169, v177, v175 dst_sel:DWORD dst_unused:UNUSED_PAD src0_sel:WORD_1 src1_sel:DWORD
	v_and_b32_sdwa v168, v171, v175 dst_sel:DWORD dst_unused:UNUSED_PAD src0_sel:WORD_1 src1_sel:DWORD
	v_add3_u32 v169, v177, v169, s21
	v_add3_u32 v168, v171, v168, s21
	v_and_b32_e32 v171, 0xffff0000, v169
	v_and_b32_sdwa v169, v170, v175 dst_sel:DWORD dst_unused:UNUSED_PAD src0_sel:WORD_1 src1_sel:DWORD
	v_and_b32_sdwa v177, v176, v175 dst_sel:DWORD dst_unused:UNUSED_PAD src0_sel:WORD_1 src1_sel:DWORD
	v_and_b32_e32 v168, 0xffff0000, v168
	v_add3_u32 v176, v176, v177, s21
	v_add3_u32 v169, v170, v169, s21
	v_or_b32_sdwa v169, v169, v168 dst_sel:DWORD dst_unused:UNUSED_PAD src0_sel:WORD_1 src1_sel:DWORD
	v_or_b32_sdwa v168, v176, v171 dst_sel:DWORD dst_unused:UNUSED_PAD src0_sel:WORD_1 src1_sel:DWORD
	global_store_dwordx4 v[182:183], v[166:169], off nt

.LBB0_233:
	s_or_b64 exec, exec, s[22:23]
	v_and_b32_sdwa v81, v15, v78 dst_sel:DWORD dst_unused:UNUSED_PAD src0_sel:WORD_1 src1_sel:DWORD
	v_and_b32_sdwa v82, v13, v78 dst_sel:DWORD dst_unused:UNUSED_PAD src0_sel:WORD_1 src1_sel:DWORD
	v_and_b32_sdwa v79, v14, v78 dst_sel:DWORD dst_unused:UNUSED_PAD src0_sel:WORD_1 src1_sel:DWORD
	s_waitcnt lgkmcnt(0)
	v_and_b32_sdwa v80, v12, v78 dst_sel:DWORD dst_unused:UNUSED_PAD src0_sel:WORD_1 src1_sel:DWORD
	v_add3_u32 v81, v15, v81, s26
	v_add3_u32 v82, v13, v82, s26
	v_lshlrev_b64 v[70:71], 12, v[70:71]
	v_add3_u32 v80, v12, v80, s26
	v_add3_u32 v79, v14, v79, s26
	v_and_b32_e32 v81, 0xffff0000, v81
	v_and_b32_e32 v82, 0xffff0000, v82
	v_lshl_add_u64 v[70:71], v[68:69], 0, v[70:71]
	v_or_b32_sdwa v81, v81, v79 dst_sel:DWORD dst_unused:UNUSED_PAD src0_sel:DWORD src1_sel:WORD_1
	v_or_b32_sdwa v80, v82, v80 dst_sel:DWORD dst_unused:UNUSED_PAD src0_sel:DWORD src1_sel:WORD_1
	global_store_dwordx2 v[70:71], v[80:81], off nt
	v_and_b32_sdwa v81, v11, v78 dst_sel:DWORD dst_unused:UNUSED_PAD src0_sel:WORD_1 src1_sel:DWORD
	v_and_b32_sdwa v82, v9, v78 dst_sel:DWORD dst_unused:UNUSED_PAD src0_sel:WORD_1 src1_sel:DWORD
	v_and_b32_sdwa v79, v10, v78 dst_sel:DWORD dst_unused:UNUSED_PAD src0_sel:WORD_1 src1_sel:DWORD
	v_and_b32_sdwa v80, v8, v78 dst_sel:DWORD dst_unused:UNUSED_PAD src0_sel:WORD_1 src1_sel:DWORD
	v_add3_u32 v81, v11, v81, s26
	v_add3_u32 v82, v9, v82, s26
	v_add3_u32 v80, v8, v80, s26
	v_add3_u32 v79, v10, v79, s26
	v_and_b32_e32 v81, 0xffff0000, v81
	v_and_b32_e32 v82, 0xffff0000, v82
	v_or_b32_sdwa v81, v81, v79 dst_sel:DWORD dst_unused:UNUSED_PAD src0_sel:DWORD src1_sel:WORD_1
	v_or_b32_sdwa v80, v82, v80 dst_sel:DWORD dst_unused:UNUSED_PAD src0_sel:DWORD src1_sel:WORD_1
	global_store_dwordx2 v[70:71], v[80:81], off offset:512 nt
	v_and_b32_sdwa v81, v7, v78 dst_sel:DWORD dst_unused:UNUSED_PAD src0_sel:WORD_1 src1_sel:DWORD
	v_and_b32_sdwa v82, v5, v78 dst_sel:DWORD dst_unused:UNUSED_PAD src0_sel:WORD_1 src1_sel:DWORD
	v_and_b32_sdwa v79, v6, v78 dst_sel:DWORD dst_unused:UNUSED_PAD src0_sel:WORD_1 src1_sel:DWORD
	v_and_b32_sdwa v80, v4, v78 dst_sel:DWORD dst_unused:UNUSED_PAD src0_sel:WORD_1 src1_sel:DWORD
	v_add3_u32 v81, v7, v81, s26
	v_add3_u32 v82, v5, v82, s26
	v_add3_u32 v80, v4, v80, s26
	v_add3_u32 v79, v6, v79, s26
	v_and_b32_e32 v81, 0xffff0000, v81
	v_and_b32_e32 v82, 0xffff0000, v82
	v_or_b32_sdwa v81, v81, v79 dst_sel:DWORD dst_unused:UNUSED_PAD src0_sel:DWORD src1_sel:WORD_1
	v_or_b32_sdwa v80, v82, v80 dst_sel:DWORD dst_unused:UNUSED_PAD src0_sel:DWORD src1_sel:WORD_1
	global_store_dwordx2 v[70:71], v[80:81], off offset:1024 nt
	v_and_b32_sdwa v81, v3, v78 dst_sel:DWORD dst_unused:UNUSED_PAD src0_sel:WORD_1 src1_sel:DWORD
	v_and_b32_sdwa v82, v1, v78 dst_sel:DWORD dst_unused:UNUSED_PAD src0_sel:WORD_1 src1_sel:DWORD
	v_and_b32_sdwa v79, v2, v78 dst_sel:DWORD dst_unused:UNUSED_PAD src0_sel:WORD_1 src1_sel:DWORD
	v_and_b32_sdwa v80, v0, v78 dst_sel:DWORD dst_unused:UNUSED_PAD src0_sel:WORD_1 src1_sel:DWORD
	v_add3_u32 v81, v3, v81, s26
	v_add3_u32 v82, v1, v82, s26
	v_add3_u32 v80, v0, v80, s26
	v_add3_u32 v79, v2, v79, s26
	v_and_b32_e32 v81, 0xffff0000, v81
	v_and_b32_e32 v82, 0xffff0000, v82
	v_or_b32_sdwa v81, v81, v79 dst_sel:DWORD dst_unused:UNUSED_PAD src0_sel:DWORD src1_sel:WORD_1
	v_or_b32_sdwa v80, v82, v80 dst_sel:DWORD dst_unused:UNUSED_PAD src0_sel:DWORD src1_sel:WORD_1
	global_store_dwordx2 v[70:71], v[80:81], off offset:1536 nt
	v_and_b32_sdwa v81, v31, v78 dst_sel:DWORD dst_unused:UNUSED_PAD src0_sel:WORD_1 src1_sel:DWORD
	v_and_b32_sdwa v82, v29, v78 dst_sel:DWORD dst_unused:UNUSED_PAD src0_sel:WORD_1 src1_sel:DWORD
	v_and_b32_sdwa v79, v30, v78 dst_sel:DWORD dst_unused:UNUSED_PAD src0_sel:WORD_1 src1_sel:DWORD
	v_and_b32_sdwa v80, v28, v78 dst_sel:DWORD dst_unused:UNUSED_PAD src0_sel:WORD_1 src1_sel:DWORD
	v_add3_u32 v81, v31, v81, s26
	v_add3_u32 v82, v29, v82, s26
	v_add3_u32 v80, v28, v80, s26
	v_add3_u32 v79, v30, v79, s26
	v_and_b32_e32 v81, 0xffff0000, v81
	v_and_b32_e32 v82, 0xffff0000, v82
	v_or_b32_sdwa v81, v81, v79 dst_sel:DWORD dst_unused:UNUSED_PAD src0_sel:DWORD src1_sel:WORD_1
	v_or_b32_sdwa v80, v82, v80 dst_sel:DWORD dst_unused:UNUSED_PAD src0_sel:DWORD src1_sel:WORD_1
	global_store_dwordx2 v[70:71], v[80:81], off offset:2048 nt
	v_and_b32_sdwa v81, v27, v78 dst_sel:DWORD dst_unused:UNUSED_PAD src0_sel:WORD_1 src1_sel:DWORD
	v_and_b32_sdwa v82, v25, v78 dst_sel:DWORD dst_unused:UNUSED_PAD src0_sel:WORD_1 src1_sel:DWORD
	v_and_b32_sdwa v79, v26, v78 dst_sel:DWORD dst_unused:UNUSED_PAD src0_sel:WORD_1 src1_sel:DWORD
	v_and_b32_sdwa v80, v24, v78 dst_sel:DWORD dst_unused:UNUSED_PAD src0_sel:WORD_1 src1_sel:DWORD
	v_add3_u32 v81, v27, v81, s26
	v_add3_u32 v82, v25, v82, s26
	v_add3_u32 v80, v24, v80, s26
	v_add3_u32 v79, v26, v79, s26
	v_and_b32_e32 v81, 0xffff0000, v81
	v_and_b32_e32 v82, 0xffff0000, v82
	v_or_b32_sdwa v81, v81, v79 dst_sel:DWORD dst_unused:UNUSED_PAD src0_sel:DWORD src1_sel:WORD_1
	v_or_b32_sdwa v80, v82, v80 dst_sel:DWORD dst_unused:UNUSED_PAD src0_sel:DWORD src1_sel:WORD_1
	global_store_dwordx2 v[70:71], v[80:81], off offset:2560 nt
	v_and_b32_sdwa v81, v23, v78 dst_sel:DWORD dst_unused:UNUSED_PAD src0_sel:WORD_1 src1_sel:DWORD
	v_and_b32_sdwa v82, v21, v78 dst_sel:DWORD dst_unused:UNUSED_PAD src0_sel:WORD_1 src1_sel:DWORD
	v_and_b32_sdwa v79, v22, v78 dst_sel:DWORD dst_unused:UNUSED_PAD src0_sel:WORD_1 src1_sel:DWORD
	v_and_b32_sdwa v80, v20, v78 dst_sel:DWORD dst_unused:UNUSED_PAD src0_sel:WORD_1 src1_sel:DWORD
	v_add3_u32 v81, v23, v81, s26
	v_add3_u32 v82, v21, v82, s26
	v_add3_u32 v80, v20, v80, s26
	v_add3_u32 v79, v22, v79, s26
	v_and_b32_e32 v81, 0xffff0000, v81
	v_and_b32_e32 v82, 0xffff0000, v82
	v_or_b32_sdwa v81, v81, v79 dst_sel:DWORD dst_unused:UNUSED_PAD src0_sel:DWORD src1_sel:WORD_1
	v_or_b32_sdwa v80, v82, v80 dst_sel:DWORD dst_unused:UNUSED_PAD src0_sel:DWORD src1_sel:WORD_1
	global_store_dwordx2 v[70:71], v[80:81], off offset:3072 nt
	v_and_b32_sdwa v81, v19, v78 dst_sel:DWORD dst_unused:UNUSED_PAD src0_sel:WORD_1 src1_sel:DWORD
	v_and_b32_sdwa v82, v17, v78 dst_sel:DWORD dst_unused:UNUSED_PAD src0_sel:WORD_1 src1_sel:DWORD
	v_and_b32_sdwa v79, v18, v78 dst_sel:DWORD dst_unused:UNUSED_PAD src0_sel:WORD_1 src1_sel:DWORD
	v_and_b32_sdwa v80, v16, v78 dst_sel:DWORD dst_unused:UNUSED_PAD src0_sel:WORD_1 src1_sel:DWORD
	v_add3_u32 v81, v19, v81, s26
	v_add3_u32 v82, v17, v82, s26
	v_add3_u32 v80, v16, v80, s26
	v_add3_u32 v79, v18, v79, s26
	v_and_b32_e32 v81, 0xffff0000, v81
	v_and_b32_e32 v82, 0xffff0000, v82
	v_or_b32_sdwa v81, v81, v79 dst_sel:DWORD dst_unused:UNUSED_PAD src0_sel:DWORD src1_sel:WORD_1
	v_or_b32_sdwa v80, v82, v80 dst_sel:DWORD dst_unused:UNUSED_PAD src0_sel:DWORD src1_sel:WORD_1
	s_andn2_b64 vcc, exec, s[20:21]
	global_store_dwordx2 v[70:71], v[80:81], off offset:3584 nt
	s_cbranch_vccnz .LBB0_226
	v_mov_b64_e32 v[16:17], v[48:49]
	v_mov_b64_e32 v[20:21], v[52:53]
	v_mov_b64_e32 v[24:25], v[56:57]
	v_mov_b64_e32 v[28:29], v[60:61]
	v_mov_b64_e32 v[0:1], v[32:33]
	v_mov_b64_e32 v[4:5], v[36:37]
	v_mov_b64_e32 v[8:9], v[40:41]
	v_mov_b64_e32 v[12:13], v[44:45]
	v_mov_b64_e32 v[18:19], v[50:51]
	v_mov_b64_e32 v[22:23], v[54:55]
	v_mov_b64_e32 v[26:27], v[58:59]
	v_mov_b64_e32 v[30:31], v[62:63]
	v_mov_b64_e32 v[2:3], v[34:35]
	v_mov_b64_e32 v[6:7], v[38:39]
	v_mov_b64_e32 v[10:11], v[42:43]
	v_mov_b64_e32 v[14:15], v[46:47]
	s_mov_b32 s8, s10
	s_branch .LBB0_226

.LBB0_887:
	s_lshl_b32 s7, s24, 8
	v_lshl_or_b32 v146, s6, 8, v150
	v_lshlrev_b32_e32 v250, 1, v146
	v_add_u32_e32 v242, s7, v148
	v_lshl_add_u32 v220, v242, 12, v250
	v_mov_b32_e32 v221, 0
	v_lshl_add_u64 v[220:221], v[220:221], 0, s[10:11]
	global_load_dwordx4 v[188:191], v[220:221], off nt
	global_load_dwordx4 v[192:195], v[220:221], off offset:256 nt
	v_add_u32_e32 v243, s7, v151
	v_lshl_add_u32 v222, v243, 12, v250
	v_mov_b32_e32 v223, 0
	v_lshl_add_u64 v[222:223], v[222:223], 0, s[10:11]
	global_load_dwordx4 v[196:199], v[222:223], off nt
	global_load_dwordx4 v[200:203], v[222:223], off offset:256 nt
	v_add_u32_e32 v244, s7, v152
	v_lshl_add_u32 v224, v244, 12, v250
	v_mov_b32_e32 v225, 0
	v_lshl_add_u64 v[224:225], v[224:225], 0, s[10:11]
	global_load_dwordx4 v[204:207], v[224:225], off nt
	global_load_dwordx4 v[208:211], v[224:225], off offset:256 nt
	v_add_u32_e32 v245, s7, v153
	v_lshl_add_u32 v226, v245, 12, v250
	v_mov_b32_e32 v227, 0
	v_lshl_add_u64 v[226:227], v[226:227], 0, s[10:11]
	global_load_dwordx4 v[212:215], v[226:227], off nt
	global_load_dwordx4 v[216:219], v[226:227], off offset:256 nt
	s_waitcnt vmcnt(7)
	v_lshlrev_b32_e32 v228, 16, v188
	v_and_b32_e32 v229, 0xffff0000, v188
	v_lshlrev_b32_e32 v230, 16, v189
	v_and_b32_e32 v231, 0xffff0000, v189
	v_lshlrev_b32_e32 v232, 16, v190
	v_and_b32_e32 v233, 0xffff0000, v190
	v_lshlrev_b32_e32 v234, 16, v191
	v_and_b32_e32 v235, 0xffff0000, v191
	v_pk_add_f32 v[228:229], v[124:125], v[228:229]
	v_pk_add_f32 v[230:231], v[126:127], v[230:231]
	v_pk_add_f32 v[232:233], v[120:121], v[232:233]
	v_pk_add_f32 v[234:235], v[122:123], v[234:235]
	v_cvt_pk_bf16_f32 v188, v228, v229
	v_cvt_pk_bf16_f32 v189, v230, v231
	v_cvt_pk_bf16_f32 v190, v232, v233
	v_cvt_pk_bf16_f32 v191, v234, v235
	v_mul_f32_e32 v236, v229, v229
	v_mul_f32_e32 v237, v231, v231
	v_mul_f32_e32 v238, v233, v233
	v_mul_f32_e32 v239, v235, v235
	v_fmac_f32_e32 v236, v228, v228
	v_fmac_f32_e32 v237, v230, v230
	v_fmac_f32_e32 v238, v232, v232
	v_fmac_f32_e32 v239, v234, v234
	global_store_dwordx4 v[220:221], v[188:191], off nt
	v_add_f32_e32 v236, v236, v237
	v_add_f32_e32 v238, v238, v239
	v_add_f32_e32 v240, v236, v238
	s_waitcnt vmcnt(7)
	v_lshlrev_b32_e32 v228, 16, v192
	v_and_b32_e32 v229, 0xffff0000, v192
	v_lshlrev_b32_e32 v230, 16, v193
	v_and_b32_e32 v231, 0xffff0000, v193
	v_lshlrev_b32_e32 v232, 16, v194
	v_and_b32_e32 v233, 0xffff0000, v194
	v_lshlrev_b32_e32 v234, 16, v195
	v_and_b32_e32 v235, 0xffff0000, v195
	v_pk_add_f32 v[228:229], v[116:117], v[228:229]
	v_pk_add_f32 v[230:231], v[118:119], v[230:231]
	v_pk_add_f32 v[232:233], v[112:113], v[232:233]
	v_pk_add_f32 v[234:235], v[114:115], v[234:235]
	v_cvt_pk_bf16_f32 v192, v228, v229
	v_cvt_pk_bf16_f32 v193, v230, v231
	v_cvt_pk_bf16_f32 v194, v232, v233
	v_cvt_pk_bf16_f32 v195, v234, v235
	v_mul_f32_e32 v236, v229, v229
	v_mul_f32_e32 v237, v231, v231
	v_mul_f32_e32 v238, v233, v233
	v_mul_f32_e32 v239, v235, v235
	v_fmac_f32_e32 v236, v228, v228
	v_fmac_f32_e32 v237, v230, v230
	v_fmac_f32_e32 v238, v232, v232
	v_fmac_f32_e32 v239, v234, v234
	global_store_dwordx4 v[220:221], v[192:195], off offset:256 nt
	v_add_f32_e32 v236, v236, v237
	v_add_f32_e32 v238, v238, v239
	v_add_f32_e32 v236, v236, v238
	v_add_f32_e32 v240, v240, v236
	v_mov_b32_e32 v241, v240
	s_nop 1
	v_permlane16_swap_b32_e32 v240, v241
	v_add_f32_e32 v240, v240, v241
	v_mov_b32_e32 v241, v240
	s_nop 1
	v_permlane32_swap_b32_e32 v240, v241
	s_and_saveexec_b64 s[24:25], s[0:1]
	v_add_f32_e32 v240, v240, v241
	ds_write_b32 v159, v240
	s_or_b64 exec, exec, s[24:25]
	v_add_u32_e32 v246, s7, v154
	v_lshl_add_u32 v220, v246, 12, v250
	v_mov_b32_e32 v221, 0
	v_lshl_add_u64 v[220:221], v[220:221], 0, s[10:11]
	global_load_dwordx4 v[188:191], v[220:221], off nt
	global_load_dwordx4 v[192:195], v[220:221], off offset:256 nt
	s_waitcnt vmcnt(9)
	v_lshlrev_b32_e32 v228, 16, v196
	v_and_b32_e32 v229, 0xffff0000, v196
	v_lshlrev_b32_e32 v230, 16, v197
	v_and_b32_e32 v231, 0xffff0000, v197
	v_lshlrev_b32_e32 v232, 16, v198
	v_and_b32_e32 v233, 0xffff0000, v198
	v_lshlrev_b32_e32 v234, 16, v199
	v_and_b32_e32 v235, 0xffff0000, v199
	v_pk_add_f32 v[228:229], v[108:109], v[228:229]
	v_pk_add_f32 v[230:231], v[110:111], v[230:231]
	v_pk_add_f32 v[232:233], v[104:105], v[232:233]
	v_pk_add_f32 v[234:235], v[106:107], v[234:235]
	v_cvt_pk_bf16_f32 v196, v228, v229
	v_cvt_pk_bf16_f32 v197, v230, v231
	v_cvt_pk_bf16_f32 v198, v232, v233
	v_cvt_pk_bf16_f32 v199, v234, v235
	v_mul_f32_e32 v236, v229, v229
	v_mul_f32_e32 v237, v231, v231
	v_mul_f32_e32 v238, v233, v233
	v_mul_f32_e32 v239, v235, v235
	v_fmac_f32_e32 v236, v228, v228
	v_fmac_f32_e32 v237, v230, v230
	v_fmac_f32_e32 v238, v232, v232
	v_fmac_f32_e32 v239, v234, v234
	global_store_dwordx4 v[222:223], v[196:199], off nt
	v_add_f32_e32 v236, v236, v237
	v_add_f32_e32 v238, v238, v239
	v_add_f32_e32 v240, v236, v238
	s_waitcnt vmcnt(9)
	v_lshlrev_b32_e32 v228, 16, v200
	v_and_b32_e32 v229, 0xffff0000, v200
	v_lshlrev_b32_e32 v230, 16, v201
	v_and_b32_e32 v231, 0xffff0000, v201
	v_lshlrev_b32_e32 v232, 16, v202
	v_and_b32_e32 v233, 0xffff0000, v202
	v_lshlrev_b32_e32 v234, 16, v203
	v_and_b32_e32 v235, 0xffff0000, v203
	v_pk_add_f32 v[228:229], v[100:101], v[228:229]
	v_pk_add_f32 v[230:231], v[102:103], v[230:231]
	v_pk_add_f32 v[232:233], v[96:97], v[232:233]
	v_pk_add_f32 v[234:235], v[98:99], v[234:235]
	v_cvt_pk_bf16_f32 v200, v228, v229
	v_cvt_pk_bf16_f32 v201, v230, v231
	v_cvt_pk_bf16_f32 v202, v232, v233
	v_cvt_pk_bf16_f32 v203, v234, v235
	v_mul_f32_e32 v236, v229, v229
	v_mul_f32_e32 v237, v231, v231
	v_mul_f32_e32 v238, v233, v233
	v_mul_f32_e32 v239, v235, v235
	v_fmac_f32_e32 v236, v228, v228
	v_fmac_f32_e32 v237, v230, v230
	v_fmac_f32_e32 v238, v232, v232
	v_fmac_f32_e32 v239, v234, v234
	global_store_dwordx4 v[222:223], v[200:203], off offset:256 nt
	v_add_f32_e32 v236, v236, v237
	v_add_f32_e32 v238, v238, v239
	v_add_f32_e32 v236, v236, v238
	v_add_f32_e32 v240, v240, v236
	v_mov_b32_e32 v241, v240
	s_nop 1
	v_permlane16_swap_b32_e32 v240, v241
	v_add_f32_e32 v240, v240, v241
	v_mov_b32_e32 v241, v240
	s_nop 1
	v_permlane32_swap_b32_e32 v240, v241
	s_and_saveexec_b64 s[24:25], s[0:1]
	v_add_f32_e32 v240, v240, v241
	ds_write_b32 v161, v240
	s_or_b64 exec, exec, s[24:25]
	v_add_u32_e32 v247, s7, v155
	v_lshl_add_u32 v222, v247, 12, v250
	v_mov_b32_e32 v223, 0
	v_lshl_add_u64 v[222:223], v[222:223], 0, s[10:11]
	global_load_dwordx4 v[196:199], v[222:223], off nt
	global_load_dwordx4 v[200:203], v[222:223], off offset:256 nt
	s_waitcnt vmcnt(11)
	v_lshlrev_b32_e32 v228, 16, v204
	v_and_b32_e32 v229, 0xffff0000, v204
	v_lshlrev_b32_e32 v230, 16, v205
	v_and_b32_e32 v231, 0xffff0000, v205
	v_lshlrev_b32_e32 v232, 16, v206
	v_and_b32_e32 v233, 0xffff0000, v206
	v_lshlrev_b32_e32 v234, 16, v207
	v_and_b32_e32 v235, 0xffff0000, v207
	v_pk_add_f32 v[228:229], v[92:93], v[228:229]
	v_pk_add_f32 v[230:231], v[94:95], v[230:231]
	v_pk_add_f32 v[232:233], v[88:89], v[232:233]
	v_pk_add_f32 v[234:235], v[90:91], v[234:235]
	v_cvt_pk_bf16_f32 v204, v228, v229
	v_cvt_pk_bf16_f32 v205, v230, v231
	v_cvt_pk_bf16_f32 v206, v232, v233
	v_cvt_pk_bf16_f32 v207, v234, v235
	v_mul_f32_e32 v236, v229, v229
	v_mul_f32_e32 v237, v231, v231
	v_mul_f32_e32 v238, v233, v233
	v_mul_f32_e32 v239, v235, v235
	v_fmac_f32_e32 v236, v228, v228
	v_fmac_f32_e32 v237, v230, v230
	v_fmac_f32_e32 v238, v232, v232
	v_fmac_f32_e32 v239, v234, v234
	global_store_dwordx4 v[224:225], v[204:207], off nt
	v_add_f32_e32 v236, v236, v237
	v_add_f32_e32 v238, v238, v239
	v_add_f32_e32 v240, v236, v238
	s_waitcnt vmcnt(11)
	v_lshlrev_b32_e32 v228, 16, v208
	v_and_b32_e32 v229, 0xffff0000, v208
	v_lshlrev_b32_e32 v230, 16, v209
	v_and_b32_e32 v231, 0xffff0000, v209
	v_lshlrev_b32_e32 v232, 16, v210
	v_and_b32_e32 v233, 0xffff0000, v210
	v_lshlrev_b32_e32 v234, 16, v211
	v_and_b32_e32 v235, 0xffff0000, v211
	v_pk_add_f32 v[228:229], v[84:85], v[228:229]
	v_pk_add_f32 v[230:231], v[86:87], v[230:231]
	v_pk_add_f32 v[232:233], v[80:81], v[232:233]
	v_pk_add_f32 v[234:235], v[82:83], v[234:235]
	v_cvt_pk_bf16_f32 v208, v228, v229
	v_cvt_pk_bf16_f32 v209, v230, v231
	v_cvt_pk_bf16_f32 v210, v232, v233
	v_cvt_pk_bf16_f32 v211, v234, v235
	v_mul_f32_e32 v236, v229, v229
	v_mul_f32_e32 v237, v231, v231
	v_mul_f32_e32 v238, v233, v233
	v_mul_f32_e32 v239, v235, v235
	v_fmac_f32_e32 v236, v228, v228
	v_fmac_f32_e32 v237, v230, v230
	v_fmac_f32_e32 v238, v232, v232
	v_fmac_f32_e32 v239, v234, v234
	global_store_dwordx4 v[224:225], v[208:211], off offset:256 nt
	v_add_f32_e32 v236, v236, v237
	v_add_f32_e32 v238, v238, v239
	v_add_f32_e32 v236, v236, v238
	v_add_f32_e32 v240, v240, v236
	v_mov_b32_e32 v241, v240
	s_nop 1
	v_permlane16_swap_b32_e32 v240, v241
	v_add_f32_e32 v240, v240, v241
	v_mov_b32_e32 v241, v240
	s_nop 1
	v_permlane32_swap_b32_e32 v240, v241
	s_and_saveexec_b64 s[24:25], s[0:1]
	v_add_f32_e32 v240, v240, v241
	ds_write_b32 v163, v240
	s_or_b64 exec, exec, s[24:25]
	v_add_u32_e32 v248, s7, v156
	v_lshl_add_u32 v224, v248, 12, v250
	v_mov_b32_e32 v225, 0
	v_lshl_add_u64 v[224:225], v[224:225], 0, s[10:11]
	global_load_dwordx4 v[204:207], v[224:225], off nt
	global_load_dwordx4 v[208:211], v[224:225], off offset:256 nt
	s_waitcnt vmcnt(13)
	v_lshlrev_b32_e32 v228, 16, v212
	v_and_b32_e32 v229, 0xffff0000, v212
	v_lshlrev_b32_e32 v230, 16, v213
	v_and_b32_e32 v231, 0xffff0000, v213
	v_lshlrev_b32_e32 v232, 16, v214
	v_and_b32_e32 v233, 0xffff0000, v214
	v_lshlrev_b32_e32 v234, 16, v215
	v_and_b32_e32 v235, 0xffff0000, v215
	v_pk_add_f32 v[228:229], v[76:77], v[228:229]
	v_pk_add_f32 v[230:231], v[78:79], v[230:231]
	v_pk_add_f32 v[232:233], v[72:73], v[232:233]
	v_pk_add_f32 v[234:235], v[74:75], v[234:235]
	v_cvt_pk_bf16_f32 v212, v228, v229
	v_cvt_pk_bf16_f32 v213, v230, v231
	v_cvt_pk_bf16_f32 v214, v232, v233
	v_cvt_pk_bf16_f32 v215, v234, v235
	v_mul_f32_e32 v236, v229, v229
	v_mul_f32_e32 v237, v231, v231
	v_mul_f32_e32 v238, v233, v233
	v_mul_f32_e32 v239, v235, v235
	v_fmac_f32_e32 v236, v228, v228
	v_fmac_f32_e32 v237, v230, v230
	v_fmac_f32_e32 v238, v232, v232
	v_fmac_f32_e32 v239, v234, v234
	global_store_dwordx4 v[226:227], v[212:215], off nt
	v_add_f32_e32 v236, v236, v237
	v_add_f32_e32 v238, v238, v239
	v_add_f32_e32 v240, v236, v238
	s_waitcnt vmcnt(13)
	v_lshlrev_b32_e32 v228, 16, v216
	v_and_b32_e32 v229, 0xffff0000, v216
	v_lshlrev_b32_e32 v230, 16, v217
	v_and_b32_e32 v231, 0xffff0000, v217
	v_lshlrev_b32_e32 v232, 16, v218
	v_and_b32_e32 v233, 0xffff0000, v218
	v_lshlrev_b32_e32 v234, 16, v219
	v_and_b32_e32 v235, 0xffff0000, v219
	v_pk_add_f32 v[228:229], v[68:69], v[228:229]
	v_pk_add_f32 v[230:231], v[70:71], v[230:231]
	v_pk_add_f32 v[232:233], v[64:65], v[232:233]
	v_pk_add_f32 v[234:235], v[66:67], v[234:235]
	v_cvt_pk_bf16_f32 v216, v228, v229
	v_cvt_pk_bf16_f32 v217, v230, v231
	v_cvt_pk_bf16_f32 v218, v232, v233
	v_cvt_pk_bf16_f32 v219, v234, v235
	v_mul_f32_e32 v236, v229, v229
	v_mul_f32_e32 v237, v231, v231
	v_mul_f32_e32 v238, v233, v233
	v_mul_f32_e32 v239, v235, v235
	v_fmac_f32_e32 v236, v228, v228
	v_fmac_f32_e32 v237, v230, v230
	v_fmac_f32_e32 v238, v232, v232
	v_fmac_f32_e32 v239, v234, v234
	global_store_dwordx4 v[226:227], v[216:219], off offset:256 nt
	v_add_f32_e32 v236, v236, v237
	v_add_f32_e32 v238, v238, v239
	v_add_f32_e32 v236, v236, v238
	v_add_f32_e32 v240, v240, v236
	v_mov_b32_e32 v241, v240
	s_nop 1
	v_permlane16_swap_b32_e32 v240, v241
	v_add_f32_e32 v240, v240, v241
	v_mov_b32_e32 v241, v240
	s_nop 1
	v_permlane32_swap_b32_e32 v240, v241
	s_and_saveexec_b64 s[24:25], s[0:1]
	v_add_f32_e32 v240, v240, v241
	ds_write_b32 v165, v240
	s_or_b64 exec, exec, s[24:25]
	v_add_u32_e32 v249, s7, v157
	v_lshl_add_u32 v226, v249, 12, v250
	v_mov_b32_e32 v227, 0
	v_lshl_add_u64 v[226:227], v[226:227], 0, s[10:11]
	global_load_dwordx4 v[212:215], v[226:227], off nt
	global_load_dwordx4 v[216:219], v[226:227], off offset:256 nt
	s_waitcnt vmcnt(13)
	v_lshlrev_b32_e32 v228, 16, v188
	v_and_b32_e32 v229, 0xffff0000, v188
	v_lshlrev_b32_e32 v230, 16, v189
	v_and_b32_e32 v231, 0xffff0000, v189
	v_lshlrev_b32_e32 v232, 16, v190
	v_and_b32_e32 v233, 0xffff0000, v190
	v_lshlrev_b32_e32 v234, 16, v191
	v_and_b32_e32 v235, 0xffff0000, v191
	v_pk_add_f32 v[228:229], v[60:61], v[228:229]
	v_pk_add_f32 v[230:231], v[62:63], v[230:231]
	v_pk_add_f32 v[232:233], v[56:57], v[232:233]
	v_pk_add_f32 v[234:235], v[58:59], v[234:235]
	v_cvt_pk_bf16_f32 v188, v228, v229
	v_cvt_pk_bf16_f32 v189, v230, v231
	v_cvt_pk_bf16_f32 v190, v232, v233
	v_cvt_pk_bf16_f32 v191, v234, v235
	v_mul_f32_e32 v236, v229, v229
	v_mul_f32_e32 v237, v231, v231
	v_mul_f32_e32 v238, v233, v233
	v_mul_f32_e32 v239, v235, v235
	v_fmac_f32_e32 v236, v228, v228
	v_fmac_f32_e32 v237, v230, v230
	v_fmac_f32_e32 v238, v232, v232
	v_fmac_f32_e32 v239, v234, v234
	global_store_dwordx4 v[220:221], v[188:191], off nt
	v_add_f32_e32 v236, v236, v237
	v_add_f32_e32 v238, v238, v239
	v_add_f32_e32 v240, v236, v238
	s_waitcnt vmcnt(13)
	v_lshlrev_b32_e32 v228, 16, v192
	v_and_b32_e32 v229, 0xffff0000, v192
	v_lshlrev_b32_e32 v230, 16, v193
	v_and_b32_e32 v231, 0xffff0000, v193
	v_lshlrev_b32_e32 v232, 16, v194
	v_and_b32_e32 v233, 0xffff0000, v194
	v_lshlrev_b32_e32 v234, 16, v195
	v_and_b32_e32 v235, 0xffff0000, v195
	v_pk_add_f32 v[228:229], v[52:53], v[228:229]
	v_pk_add_f32 v[230:231], v[54:55], v[230:231]
	v_pk_add_f32 v[232:233], v[48:49], v[232:233]
	v_pk_add_f32 v[234:235], v[50:51], v[234:235]
	v_cvt_pk_bf16_f32 v192, v228, v229
	v_cvt_pk_bf16_f32 v193, v230, v231
	v_cvt_pk_bf16_f32 v194, v232, v233
	v_cvt_pk_bf16_f32 v195, v234, v235
	v_mul_f32_e32 v236, v229, v229
	v_mul_f32_e32 v237, v231, v231
	v_mul_f32_e32 v238, v233, v233
	v_mul_f32_e32 v239, v235, v235
	v_fmac_f32_e32 v236, v228, v228
	v_fmac_f32_e32 v237, v230, v230
	v_fmac_f32_e32 v238, v232, v232
	v_fmac_f32_e32 v239, v234, v234
	global_store_dwordx4 v[220:221], v[192:195], off offset:256 nt
	v_add_f32_e32 v236, v236, v237
	v_add_f32_e32 v238, v238, v239
	v_add_f32_e32 v236, v236, v238
	v_add_f32_e32 v240, v240, v236
	v_mov_b32_e32 v241, v240
	s_nop 1
	v_permlane16_swap_b32_e32 v240, v241
	v_add_f32_e32 v240, v240, v241
	v_mov_b32_e32 v241, v240
	s_nop 1
	v_permlane32_swap_b32_e32 v240, v241
	s_and_saveexec_b64 s[24:25], s[0:1]
	v_add_f32_e32 v240, v240, v241
	ds_write_b32 v167, v240
	s_or_b64 exec, exec, s[24:25]
	s_waitcnt vmcnt(11)
	v_lshlrev_b32_e32 v228, 16, v196
	v_and_b32_e32 v229, 0xffff0000, v196
	v_lshlrev_b32_e32 v230, 16, v197
	v_and_b32_e32 v231, 0xffff0000, v197
	v_lshlrev_b32_e32 v232, 16, v198
	v_and_b32_e32 v233, 0xffff0000, v198
	v_lshlrev_b32_e32 v234, 16, v199
	v_and_b32_e32 v235, 0xffff0000, v199
	v_pk_add_f32 v[228:229], v[44:45], v[228:229]
	v_pk_add_f32 v[230:231], v[46:47], v[230:231]
	v_pk_add_f32 v[232:233], v[40:41], v[232:233]
	v_pk_add_f32 v[234:235], v[42:43], v[234:235]
	v_cvt_pk_bf16_f32 v196, v228, v229
	v_cvt_pk_bf16_f32 v197, v230, v231
	v_cvt_pk_bf16_f32 v198, v232, v233
	v_cvt_pk_bf16_f32 v199, v234, v235
	v_mul_f32_e32 v236, v229, v229
	v_mul_f32_e32 v237, v231, v231
	v_mul_f32_e32 v238, v233, v233
	v_mul_f32_e32 v239, v235, v235
	v_fmac_f32_e32 v236, v228, v228
	v_fmac_f32_e32 v237, v230, v230
	v_fmac_f32_e32 v238, v232, v232
	v_fmac_f32_e32 v239, v234, v234
	global_store_dwordx4 v[222:223], v[196:199], off nt
	v_add_f32_e32 v236, v236, v237
	v_add_f32_e32 v238, v238, v239
	v_add_f32_e32 v240, v236, v238
	s_waitcnt vmcnt(11)
	v_lshlrev_b32_e32 v228, 16, v200
	v_and_b32_e32 v229, 0xffff0000, v200
	v_lshlrev_b32_e32 v230, 16, v201
	v_and_b32_e32 v231, 0xffff0000, v201
	v_lshlrev_b32_e32 v232, 16, v202
	v_and_b32_e32 v233, 0xffff0000, v202
	v_lshlrev_b32_e32 v234, 16, v203
	v_and_b32_e32 v235, 0xffff0000, v203
	v_pk_add_f32 v[228:229], v[36:37], v[228:229]
	v_pk_add_f32 v[230:231], v[38:39], v[230:231]
	v_pk_add_f32 v[232:233], v[32:33], v[232:233]
	v_pk_add_f32 v[234:235], v[34:35], v[234:235]
	v_cvt_pk_bf16_f32 v200, v228, v229
	v_cvt_pk_bf16_f32 v201, v230, v231
	v_cvt_pk_bf16_f32 v202, v232, v233
	v_cvt_pk_bf16_f32 v203, v234, v235
	v_mul_f32_e32 v236, v229, v229
	v_mul_f32_e32 v237, v231, v231
	v_mul_f32_e32 v238, v233, v233
	v_mul_f32_e32 v239, v235, v235
	v_fmac_f32_e32 v236, v228, v228
	v_fmac_f32_e32 v237, v230, v230
	v_fmac_f32_e32 v238, v232, v232
	v_fmac_f32_e32 v239, v234, v234
	global_store_dwordx4 v[222:223], v[200:203], off offset:256 nt
	v_add_f32_e32 v236, v236, v237
	v_add_f32_e32 v238, v238, v239
	v_add_f32_e32 v236, v236, v238
	v_add_f32_e32 v240, v240, v236
	v_mov_b32_e32 v241, v240
	s_nop 1
	v_permlane16_swap_b32_e32 v240, v241
	v_add_f32_e32 v240, v240, v241
	v_mov_b32_e32 v241, v240
	s_nop 1
	v_permlane32_swap_b32_e32 v240, v241
	s_and_saveexec_b64 s[24:25], s[0:1]
	v_add_f32_e32 v240, v240, v241
	ds_write_b32 v169, v240
	s_or_b64 exec, exec, s[24:25]
	s_waitcnt vmcnt(9)
	v_lshlrev_b32_e32 v228, 16, v204
	v_and_b32_e32 v229, 0xffff0000, v204
	v_lshlrev_b32_e32 v230, 16, v205
	v_and_b32_e32 v231, 0xffff0000, v205
	v_lshlrev_b32_e32 v232, 16, v206
	v_and_b32_e32 v233, 0xffff0000, v206
	v_lshlrev_b32_e32 v234, 16, v207
	v_and_b32_e32 v235, 0xffff0000, v207
	v_pk_add_f32 v[228:229], v[28:29], v[228:229]
	v_pk_add_f32 v[230:231], v[30:31], v[230:231]
	v_pk_add_f32 v[232:233], v[24:25], v[232:233]
	v_pk_add_f32 v[234:235], v[26:27], v[234:235]
	v_cvt_pk_bf16_f32 v204, v228, v229
	v_cvt_pk_bf16_f32 v205, v230, v231
	v_cvt_pk_bf16_f32 v206, v232, v233
	v_cvt_pk_bf16_f32 v207, v234, v235
	v_mul_f32_e32 v236, v229, v229
	v_mul_f32_e32 v237, v231, v231
	v_mul_f32_e32 v238, v233, v233
	v_mul_f32_e32 v239, v235, v235
	v_fmac_f32_e32 v236, v228, v228
	v_fmac_f32_e32 v237, v230, v230
	v_fmac_f32_e32 v238, v232, v232
	v_fmac_f32_e32 v239, v234, v234
	global_store_dwordx4 v[224:225], v[204:207], off nt
	v_add_f32_e32 v236, v236, v237
	v_add_f32_e32 v238, v238, v239
	v_add_f32_e32 v240, v236, v238
	s_waitcnt vmcnt(9)
	v_lshlrev_b32_e32 v228, 16, v208
	v_and_b32_e32 v229, 0xffff0000, v208
	v_lshlrev_b32_e32 v230, 16, v209
	v_and_b32_e32 v231, 0xffff0000, v209
	v_lshlrev_b32_e32 v232, 16, v210
	v_and_b32_e32 v233, 0xffff0000, v210
	v_lshlrev_b32_e32 v234, 16, v211
	v_and_b32_e32 v235, 0xffff0000, v211
	v_pk_add_f32 v[228:229], v[20:21], v[228:229]
	v_pk_add_f32 v[230:231], v[22:23], v[230:231]
	v_pk_add_f32 v[232:233], v[16:17], v[232:233]
	v_pk_add_f32 v[234:235], v[18:19], v[234:235]
	v_cvt_pk_bf16_f32 v208, v228, v229
	v_cvt_pk_bf16_f32 v209, v230, v231
	v_cvt_pk_bf16_f32 v210, v232, v233
	v_cvt_pk_bf16_f32 v211, v234, v235
	v_mul_f32_e32 v236, v229, v229
	v_mul_f32_e32 v237, v231, v231
	v_mul_f32_e32 v238, v233, v233
	v_mul_f32_e32 v239, v235, v235
	v_fmac_f32_e32 v236, v228, v228
	v_fmac_f32_e32 v237, v230, v230
	v_fmac_f32_e32 v238, v232, v232
	v_fmac_f32_e32 v239, v234, v234
	global_store_dwordx4 v[224:225], v[208:211], off offset:256 nt
	v_add_f32_e32 v236, v236, v237
	v_add_f32_e32 v238, v238, v239
	v_add_f32_e32 v236, v236, v238
	v_add_f32_e32 v240, v240, v236
	v_mov_b32_e32 v241, v240
	s_nop 1
	v_permlane16_swap_b32_e32 v240, v241
	v_add_f32_e32 v240, v240, v241
	v_mov_b32_e32 v241, v240
	s_nop 1
	v_permlane32_swap_b32_e32 v240, v241
	s_and_saveexec_b64 s[24:25], s[0:1]
	v_add_f32_e32 v240, v240, v241
	ds_write_b32 v171, v240
	s_or_b64 exec, exec, s[24:25]
	s_waitcnt vmcnt(7)
	v_lshlrev_b32_e32 v228, 16, v212
	v_and_b32_e32 v229, 0xffff0000, v212
	v_lshlrev_b32_e32 v230, 16, v213
	v_and_b32_e32 v231, 0xffff0000, v213
	v_lshlrev_b32_e32 v232, 16, v214
	v_and_b32_e32 v233, 0xffff0000, v214
	v_lshlrev_b32_e32 v234, 16, v215
	v_and_b32_e32 v235, 0xffff0000, v215
	v_pk_add_f32 v[228:229], v[12:13], v[228:229]
	v_pk_add_f32 v[230:231], v[14:15], v[230:231]
	v_pk_add_f32 v[232:233], v[8:9], v[232:233]
	v_pk_add_f32 v[234:235], v[10:11], v[234:235]
	v_cvt_pk_bf16_f32 v212, v228, v229
	v_cvt_pk_bf16_f32 v213, v230, v231
	v_cvt_pk_bf16_f32 v214, v232, v233
	v_cvt_pk_bf16_f32 v215, v234, v235
	v_mul_f32_e32 v236, v229, v229
	v_mul_f32_e32 v237, v231, v231
	v_mul_f32_e32 v238, v233, v233
	v_mul_f32_e32 v239, v235, v235
	v_fmac_f32_e32 v236, v228, v228
	v_fmac_f32_e32 v237, v230, v230
	v_fmac_f32_e32 v238, v232, v232
	v_fmac_f32_e32 v239, v234, v234
	global_store_dwordx4 v[226:227], v[212:215], off nt
	v_add_f32_e32 v236, v236, v237
	v_add_f32_e32 v238, v238, v239
	v_add_f32_e32 v240, v236, v238
	s_waitcnt vmcnt(7)
	v_lshlrev_b32_e32 v228, 16, v216
	v_and_b32_e32 v229, 0xffff0000, v216
	v_lshlrev_b32_e32 v230, 16, v217
	v_and_b32_e32 v231, 0xffff0000, v217
	v_lshlrev_b32_e32 v232, 16, v218
	v_and_b32_e32 v233, 0xffff0000, v218
	v_lshlrev_b32_e32 v234, 16, v219
	v_and_b32_e32 v235, 0xffff0000, v219
	v_pk_add_f32 v[228:229], v[4:5], v[228:229]
	v_pk_add_f32 v[230:231], v[6:7], v[230:231]
	v_pk_add_f32 v[232:233], v[0:1], v[232:233]
	v_pk_add_f32 v[234:235], v[2:3], v[234:235]
	v_cvt_pk_bf16_f32 v216, v228, v229
	v_cvt_pk_bf16_f32 v217, v230, v231
	v_cvt_pk_bf16_f32 v218, v232, v233
	v_cvt_pk_bf16_f32 v219, v234, v235
	v_mul_f32_e32 v236, v229, v229
	v_mul_f32_e32 v237, v231, v231
	v_mul_f32_e32 v238, v233, v233
	v_mul_f32_e32 v239, v235, v235
	v_fmac_f32_e32 v236, v228, v228
	v_fmac_f32_e32 v237, v230, v230
	v_fmac_f32_e32 v238, v232, v232
	v_fmac_f32_e32 v239, v234, v234
	global_store_dwordx4 v[226:227], v[216:219], off offset:256 nt
	v_add_f32_e32 v236, v236, v237
	v_add_f32_e32 v238, v238, v239
	v_add_f32_e32 v236, v236, v238
	v_add_f32_e32 v240, v240, v236
	v_mov_b32_e32 v241, v240
	s_nop 1
	v_permlane16_swap_b32_e32 v240, v241
	v_add_f32_e32 v240, v240, v241
	v_mov_b32_e32 v241, v240
	s_nop 1
	v_permlane32_swap_b32_e32 v240, v241
	s_and_saveexec_b64 s[24:25], s[0:1]
	v_add_f32_e32 v240, v240, v241
	ds_write_b32 v173, v240
	s_or_b64 exec, exec, s[24:25]
	v_mov_b32_e32 v144, v242
	v_mov_b32_e32 v145, 0
	v_mov_b32_e32 v112, v243
	v_mov_b32_e32 v113, 0
	v_mov_b32_e32 v96, v244
	v_mov_b32_e32 v97, 0
	v_mov_b32_e32 v80, v245
	v_mov_b32_e32 v81, 0
	v_mov_b32_e32 v64, v246
	v_mov_b32_e32 v65, 0
	v_mov_b32_e32 v48, v247
	v_mov_b32_e32 v49, 0
	v_mov_b32_e32 v32, v248
	v_mov_b32_e32 v33, 0
	v_mov_b32_e32 v16, v249
	v_mov_b32_e32 v17, 0
	s_waitcnt lgkmcnt(0)
	s_barrier
	s_and_saveexec_b64 s[24:25], s[2:3]
	s_cbranch_execz .LBB0_905
	ds_read_b128 v[0:3], v158
	ds_read_b128 v[4:7], v160
	s_ashr_i32 s7, s6, 31
	s_lshl_b64 s[6:7], s[6:7], 2
	s_add_u32 s6, s44, s6
	s_waitcnt lgkmcnt(1)
	v_add_f32_e32 v0, v0, v1
	v_add_f32_e32 v1, v2, v3
	s_addc_u32 s7, s45, s7
	v_add_f32_e32 v2, v0, v1
	v_lshlrev_b64 v[0:1], 5, v[144:145]
	v_lshl_add_u64 v[0:1], s[6:7], 0, v[0:1]
	global_store_dword v[0:1], v2, off
	s_waitcnt lgkmcnt(0)
	v_add_f32_e32 v0, v4, v5
	v_add_f32_e32 v1, v6, v7
	v_add_f32_e32 v6, v0, v1
	ds_read_b128 v[0:3], v162
	v_lshlrev_b64 v[4:5], 5, v[112:113]
	v_lshl_add_u64 v[4:5], s[6:7], 0, v[4:5]
	global_store_dword v[4:5], v6, off
	ds_read_b128 v[4:7], v164
	s_waitcnt lgkmcnt(1)
	v_add_f32_e32 v0, v0, v1
	v_add_f32_e32 v1, v2, v3
	v_add_f32_e32 v2, v0, v1
	v_lshlrev_b64 v[0:1], 5, v[96:97]
	v_lshl_add_u64 v[0:1], s[6:7], 0, v[0:1]
	global_store_dword v[0:1], v2, off
	s_waitcnt lgkmcnt(0)
	v_add_f32_e32 v0, v4, v5
	v_add_f32_e32 v1, v6, v7
	v_add_f32_e32 v6, v0, v1
	ds_read_b128 v[0:3], v166
	v_lshlrev_b64 v[4:5], 5, v[80:81]
	v_lshl_add_u64 v[4:5], s[6:7], 0, v[4:5]
	global_store_dword v[4:5], v6, off
	ds_read_b128 v[4:7], v168
	s_waitcnt lgkmcnt(1)
	v_add_f32_e32 v0, v0, v1
	v_add_f32_e32 v1, v2, v3
	v_add_f32_e32 v2, v0, v1
	v_lshlrev_b64 v[0:1], 5, v[64:65]
	v_lshl_add_u64 v[0:1], s[6:7], 0, v[0:1]
	global_store_dword v[0:1], v2, off
	s_waitcnt lgkmcnt(0)
	v_add_f32_e32 v0, v4, v5
	v_add_f32_e32 v1, v6, v7
	v_add_f32_e32 v6, v0, v1
	ds_read_b128 v[0:3], v170
	v_lshlrev_b64 v[4:5], 5, v[48:49]
	v_lshl_add_u64 v[4:5], s[6:7], 0, v[4:5]
	global_store_dword v[4:5], v6, off
	ds_read_b128 v[4:7], v172
	s_waitcnt lgkmcnt(1)
	v_add_f32_e32 v0, v0, v1
	v_add_f32_e32 v1, v2, v3
	v_add_f32_e32 v2, v0, v1
	v_lshlrev_b64 v[0:1], 5, v[32:33]
	v_lshl_add_u64 v[0:1], s[6:7], 0, v[0:1]
	global_store_dword v[0:1], v2, off
	s_waitcnt lgkmcnt(0)
	v_add_f32_e32 v0, v4, v5
	v_add_f32_e32 v1, v6, v7
	v_add_f32_e32 v2, v0, v1
	v_lshlrev_b64 v[0:1], 5, v[16:17]
	v_lshl_add_u64 v[0:1], s[6:7], 0, v[0:1]
	global_store_dword v[0:1], v2, off
